# P9 conv epilogue: both column halves of a row paired by permlane16 swaps into one 16-byte store (8 instead of 16 stores per unit)
# speedup vs baseline: 1.0025x; 1.0014x over previous
; __device__ __forceinline__ void st_bf4(bf16_t* p, f32x4 v) { u32x2 w; w.x = pk2(v[0], v[1]); w.y = pk2(v[2], v[3]); *(u32x2*)p = w; }
; __device__ __forceinline__ float sigmoidf_(float x) { return __builtin_amdgcn_rcpf(1.f + __expf(-x)); }
; __device__ __forceinline__ float dpp_ror1(float v) { return __int_as_float(__builtin_amdgcn_update_dpp(0, __float_as_int(v), 0x121, 0xf, 0xf, false)); }
; __device__ __forceinline__ float dpp_rol1(float v) { return __int_as_float(__builtin_amdgcn_update_dpp(0, __float_as_int(v), 0x12F, 0xf, 0xf, false)); }
;     __device__ __forceinline__ void tile(const f32x4 (&acc)[2][2][4][2], const Unit& u, int wr, int wc, int fr, int fq) const {
;     ...
;             const int cv = 128 * u.pn + 32 * wc + 16 * n + 4 * fq, cg = FF + cv;
;             const f32x4 wv0 = *(const f32x4*)(cw + cv), wv1 = *(const f32x4*)(cw + F2 + cv), wv2 = *(const f32x4*)(cw + 2 * F2 + cv), bv = *(const f32x4*)(cb + cv);
;             const f32x4 wg0 = *(const f32x4*)(cw + cg), wg1 = *(const f32x4*)(cw + F2 + cg), wg2 = *(const f32x4*)(cw + 2 * F2 + cg), bg = *(const f32x4*)(cb + cg);
; #pragma unroll
;             for (int ai = 0; ai < 2; ++ai)
; #pragma unroll
;                 for (int m = 0; m < 4; ++m) {
;                     f32x4 r;
; #pragma unroll
;                     for (int i = 0; i < 4; ++i) {
;                         const float xv = acc[ai][0][m][n][i], xg = acc[ai][1][m][n][i];
;                         const float uv = m > 0 ? acc[ai][0][m > 0 ? m - 1 : 0][n][i] : 0.f, ug = m > 0 ? acc[ai][1][m > 0 ? m - 1 : 0][n][i] : 0.f;
;                         const float dv = m < 3 ? acc[ai][0][m < 3 ? m + 1 : 3][n][i] : 0.f, dg = m < 3 ? acc[ai][1][m < 3 ? m + 1 : 3][n][i] : 0.f;
;                         const float pv = dpp_ror1(fr == 15 ? uv : xv), pg = dpp_ror1(fr == 15 ? ug : xg);
;                         const float nv = dpp_rol1(fr == 0 ? dv : xv), ng = dpp_rol1(fr == 0 ? dg : xg);
;                         const float yv = wv0[i] * pv + wv1[i] * xv + wv2[i] * nv + bv[i];
;                         const float yg = wg0[i] * pg + wg1[i] * xg + wg2[i] * ng + bg[i];
;                         r[i] = yg * sigmoidf_(yg) * yv;
;                     }
;                     st_bf4(ACT + (size_t)(u.pm * BM + ai * HALF + wr * 64 + m * 16 + fr) * FF + cv, r);
.Lp9c_havepre:
	global_load_dwordx4 v[120:123], v171, s[14:15]
	global_load_dwordx4 v[124:127], v171, s[58:59]
	global_load_dwordx4 v[128:131], v172, s[56:57] offset:64
	global_load_dwordx4 v[132:135], v172, s[12:13] offset:64
	global_load_dwordx4 v[136:139], v172, s[14:15] offset:64
	global_load_dwordx4 v[140:143], v172, s[58:59] offset:64
	global_load_dwordx4 v[144:147], v171, s[56:57] offset:64
	global_load_dwordx4 v[148:151], v171, s[12:13] offset:64
	global_load_dwordx4 v[208:211], v171, s[14:15] offset:64
	global_load_dwordx4 v[212:215], v171, s[58:59] offset:64
	s_lshl_b32 s17, s26, 8
	v_and_b32_e32 v173, 64, v195
	v_and_b32_e32 v174, 15, v195
	v_lshl_add_u32 v173, v174, 2, v173
	v_add_u32_e32 v173, s17, v173
	v_mul_u32_u24_e32 v173, 0x2c00, v173
	v_lshl_add_u32 v173, v170, 1, v173
	v_add_u32_e32 v174, 0x160000, v173
	v_bfe_u32 v175, v204, 2, 2
	v_and_b32_e32 v168, 1, v175
	v_lshrrev_b32_e32 v169, 1, v175
	v_lshlrev_b32_e32 v168, 4, v168
	v_lshl_add_u32 v168, v169, 3, v168
	v_and_b32_e32 v169, 0x60, v204
	v_add_u32_e32 v168, v168, v169
	v_sub_u32_e32 v168, v168, v204
	v_lshl_add_u32 v173, v168, 1, v173
	v_lshl_add_u32 v174, v168, 1, v174
	s_cmp_lg_u32 s98, 0
	s_cbranch_scc1 .Lp9c_nowait
	s_waitcnt vmcnt(10)
.Lp9c_nowait:
	v_mov_b32_dpp v216, v96 row_shr:1 row_mask:0xf bank_mask:0xf bound_ctrl:1
	v_mov_b32_dpp v217, v97 row_shr:1 row_mask:0xf bank_mask:0xf bound_ctrl:1
	v_mov_b32_dpp v218, v98 row_shr:1 row_mask:0xf bank_mask:0xf bound_ctrl:1
	v_mov_b32_dpp v219, v99 row_shr:1 row_mask:0xf bank_mask:0xf bound_ctrl:1
	v_mov_b32_dpp v220, v152 row_shl:1 row_mask:0xf bank_mask:0xf bound_ctrl:1
	v_mov_b32_dpp v221, v153 row_shl:1 row_mask:0xf bank_mask:0xf bound_ctrl:1
	v_mov_b32_dpp v222, v154 row_shl:1 row_mask:0xf bank_mask:0xf bound_ctrl:1
	v_mov_b32_dpp v223, v155 row_shl:1 row_mask:0xf bank_mask:0xf bound_ctrl:1
	v_pk_mul_f32 v[176:177], v[152:153], v[234:235]
	v_pk_mul_f32 v[178:179], v[154:155], v[236:237]
	v_pk_mul_f32 v[180:181], v[112:113], v[234:235]
	v_pk_mul_f32 v[182:183], v[114:115], v[236:237]
	v_pk_mul_f32 v[184:185], v[104:105], v[234:235]
	v_pk_mul_f32 v[186:187], v[106:107], v[236:237]
	v_pk_mul_f32 v[224:225], v[96:97], v[234:235]
	v_pk_mul_f32 v[226:227], v[98:99], v[236:237]
	v_pk_fma_f32 v[176:177], v[230:231], v[216:217], v[176:177]
	v_pk_fma_f32 v[178:179], v[232:233], v[218:219], v[178:179]
	v_pk_fma_f32 v[180:181], v[230:231], v[152:153], v[180:181]
	v_pk_fma_f32 v[182:183], v[232:233], v[154:155], v[182:183]
	v_pk_fma_f32 v[184:185], v[230:231], v[112:113], v[184:185]
	v_pk_fma_f32 v[186:187], v[232:233], v[114:115], v[186:187]
	v_pk_fma_f32 v[224:225], v[230:231], v[104:105], v[224:225]
	v_pk_fma_f32 v[226:227], v[232:233], v[106:107], v[226:227]
	v_pk_fma_f32 v[176:177], v[238:239], v[112:113], v[176:177]
	v_pk_fma_f32 v[178:179], v[240:241], v[114:115], v[178:179]
	v_pk_fma_f32 v[180:181], v[238:239], v[104:105], v[180:181]
	v_pk_fma_f32 v[182:183], v[240:241], v[106:107], v[182:183]
	v_pk_fma_f32 v[184:185], v[238:239], v[96:97], v[184:185]
	v_pk_fma_f32 v[186:187], v[240:241], v[98:99], v[186:187]
	v_pk_fma_f32 v[224:225], v[238:239], v[220:221], v[224:225]
	v_pk_fma_f32 v[226:227], v[240:241], v[222:223], v[226:227]
	v_pk_add_f32 v[176:177], v[242:243], v[176:177]
	v_pk_add_f32 v[178:179], v[244:245], v[178:179]
	v_pk_add_f32 v[180:181], v[242:243], v[180:181]
	v_pk_add_f32 v[182:183], v[244:245], v[182:183]
	v_pk_add_f32 v[184:185], v[242:243], v[184:185]
	v_pk_add_f32 v[186:187], v[244:245], v[186:187]
	v_pk_add_f32 v[224:225], v[242:243], v[224:225]
	v_pk_add_f32 v[226:227], v[244:245], v[226:227]
	v_mov_b32_dpp v216, v100 row_shr:1 row_mask:0xf bank_mask:0xf bound_ctrl:1
	v_mov_b32_dpp v217, v101 row_shr:1 row_mask:0xf bank_mask:0xf bound_ctrl:1
	v_mov_b32_dpp v218, v102 row_shr:1 row_mask:0xf bank_mask:0xf bound_ctrl:1
	v_mov_b32_dpp v219, v103 row_shr:1 row_mask:0xf bank_mask:0xf bound_ctrl:1
	v_mov_b32_dpp v220, v156 row_shl:1 row_mask:0xf bank_mask:0xf bound_ctrl:1
	v_mov_b32_dpp v221, v157 row_shl:1 row_mask:0xf bank_mask:0xf bound_ctrl:1
	v_mov_b32_dpp v222, v158 row_shl:1 row_mask:0xf bank_mask:0xf bound_ctrl:1
	v_mov_b32_dpp v223, v159 row_shl:1 row_mask:0xf bank_mask:0xf bound_ctrl:1
	v_pk_mul_f32 v[152:153], v[156:157], v[250:251]
	v_pk_mul_f32 v[154:155], v[158:159], v[252:253]
	v_pk_mul_f32 v[112:113], v[116:117], v[250:251]
	v_pk_mul_f32 v[114:115], v[118:119], v[252:253]
	v_pk_mul_f32 v[104:105], v[108:109], v[250:251]
	v_pk_mul_f32 v[106:107], v[110:111], v[252:253]
	v_pk_mul_f32 v[96:97], v[100:101], v[250:251]
	v_pk_mul_f32 v[98:99], v[102:103], v[252:253]
	v_pk_fma_f32 v[152:153], v[246:247], v[216:217], v[152:153]
	v_pk_fma_f32 v[154:155], v[248:249], v[218:219], v[154:155]
	v_pk_fma_f32 v[112:113], v[246:247], v[156:157], v[112:113]
	v_pk_fma_f32 v[114:115], v[248:249], v[158:159], v[114:115]
	v_pk_fma_f32 v[104:105], v[246:247], v[116:117], v[104:105]
	v_pk_fma_f32 v[106:107], v[248:249], v[118:119], v[106:107]
	v_pk_fma_f32 v[96:97], v[246:247], v[108:109], v[96:97]
	v_pk_fma_f32 v[98:99], v[248:249], v[110:111], v[98:99]
	s_waitcnt vmcnt(8)
; __device__ __forceinline__ void st_bf4(bf16_t* p, f32x4 v) { u32x2 w; w.x = pk2(v[0], v[1]); w.y = pk2(v[2], v[3]); *(u32x2*)p = w; }
; __device__ __forceinline__ float sigmoidf_(float x) { return __builtin_amdgcn_rcpf(1.f + __expf(-x)); }
; __device__ __forceinline__ float dpp_ror1(float v) { return __int_as_float(__builtin_amdgcn_update_dpp(0, __float_as_int(v), 0x121, 0xf, 0xf, false)); }
; __device__ __forceinline__ float dpp_rol1(float v) { return __int_as_float(__builtin_amdgcn_update_dpp(0, __float_as_int(v), 0x12F, 0xf, 0xf, false)); }
;     __device__ __forceinline__ void tile(const f32x4 (&acc)[2][2][4][2], const Unit& u, int wr, int wc, int fr, int fq) const {
;     ...
;                     for (int i = 0; i < 4; ++i) {
;                         const float xv = acc[ai][0][m][n][i], xg = acc[ai][1][m][n][i];
;                         const float uv = m > 0 ? acc[ai][0][m > 0 ? m - 1 : 0][n][i] : 0.f, ug = m > 0 ? acc[ai][1][m > 0 ? m - 1 : 0][n][i] : 0.f;
;                         const float dv = m < 3 ? acc[ai][0][m < 3 ? m + 1 : 3][n][i] : 0.f, dg = m < 3 ? acc[ai][1][m < 3 ? m + 1 : 3][n][i] : 0.f;
;                         const float pv = dpp_ror1(fr == 15 ? uv : xv), pg = dpp_ror1(fr == 15 ? ug : xg);
;                         const float nv = dpp_rol1(fr == 0 ? dv : xv), ng = dpp_rol1(fr == 0 ? dg : xg);
;                         const float yv = wv0[i] * pv + wv1[i] * xv + wv2[i] * nv + bv[i];
;                         const float yg = wg0[i] * pg + wg1[i] * xg + wg2[i] * ng + bg[i];
;                         r[i] = yg * sigmoidf_(yg) * yv;
;                     }
;                     st_bf4(ACT + (size_t)(u.pm * BM + ai * HALF + wr * 64 + m * 16 + fr) * FF + cv, r);
	v_pk_fma_f32 v[152:153], v[120:121], v[116:117], v[152:153]
	v_pk_fma_f32 v[154:155], v[122:123], v[118:119], v[154:155]
	v_pk_fma_f32 v[112:113], v[120:121], v[108:109], v[112:113]
	v_pk_fma_f32 v[114:115], v[122:123], v[110:111], v[114:115]
	v_pk_fma_f32 v[104:105], v[120:121], v[100:101], v[104:105]
	v_pk_fma_f32 v[106:107], v[122:123], v[102:103], v[106:107]
	v_pk_fma_f32 v[96:97], v[120:121], v[220:221], v[96:97]
	v_pk_fma_f32 v[98:99], v[122:123], v[222:223], v[98:99]
	v_pk_add_f32 v[152:153], v[124:125], v[152:153]
	v_pk_add_f32 v[154:155], v[126:127], v[154:155]
	v_pk_add_f32 v[112:113], v[124:125], v[112:113]
	v_pk_add_f32 v[114:115], v[126:127], v[114:115]
	v_pk_add_f32 v[104:105], v[124:125], v[104:105]
	v_pk_add_f32 v[106:107], v[126:127], v[106:107]
	v_pk_add_f32 v[96:97], v[124:125], v[96:97]
	v_pk_add_f32 v[98:99], v[126:127], v[98:99]
	v_mul_f32_e32 v156, 0xbfb8aa3b, v176
	v_mul_f32_e32 v157, 0xbfb8aa3b, v177
	v_mul_f32_e32 v158, 0xbfb8aa3b, v178
	v_mul_f32_e32 v159, 0xbfb8aa3b, v179
	v_mul_f32_e32 v116, 0xbfb8aa3b, v180
	v_mul_f32_e32 v117, 0xbfb8aa3b, v181
	v_mul_f32_e32 v118, 0xbfb8aa3b, v182
	v_mul_f32_e32 v119, 0xbfb8aa3b, v183
	v_mul_f32_e32 v108, 0xbfb8aa3b, v184
	v_mul_f32_e32 v109, 0xbfb8aa3b, v185
	v_mul_f32_e32 v110, 0xbfb8aa3b, v186
	v_mul_f32_e32 v111, 0xbfb8aa3b, v187
	v_mul_f32_e32 v100, 0xbfb8aa3b, v224
	v_mul_f32_e32 v101, 0xbfb8aa3b, v225
	v_mul_f32_e32 v102, 0xbfb8aa3b, v226
	v_mul_f32_e32 v103, 0xbfb8aa3b, v227
	v_exp_f32_e32 v156, v156
	v_exp_f32_e32 v157, v157
	v_exp_f32_e32 v158, v158
	v_exp_f32_e32 v159, v159
	v_exp_f32_e32 v116, v116
	v_exp_f32_e32 v117, v117
	v_exp_f32_e32 v118, v118
	v_exp_f32_e32 v119, v119
	v_exp_f32_e32 v108, v108
	v_exp_f32_e32 v109, v109
	v_exp_f32_e32 v110, v110
	v_exp_f32_e32 v111, v111
	v_exp_f32_e32 v100, v100
	v_exp_f32_e32 v101, v101
	v_exp_f32_e32 v102, v102
	v_exp_f32_e32 v103, v103
	v_add_f32_e32 v156, 1.0, v156
	v_add_f32_e32 v157, 1.0, v157
	v_add_f32_e32 v158, 1.0, v158
	v_add_f32_e32 v159, 1.0, v159
	v_add_f32_e32 v116, 1.0, v116
	v_add_f32_e32 v117, 1.0, v117
	v_add_f32_e32 v118, 1.0, v118
	v_add_f32_e32 v119, 1.0, v119
	v_add_f32_e32 v108, 1.0, v108
	v_add_f32_e32 v109, 1.0, v109
	v_add_f32_e32 v110, 1.0, v110
	v_add_f32_e32 v111, 1.0, v111
	v_add_f32_e32 v100, 1.0, v100
	v_add_f32_e32 v101, 1.0, v101
	v_add_f32_e32 v102, 1.0, v102
	v_add_f32_e32 v103, 1.0, v103
	v_rcp_f32_e32 v156, v156
	v_rcp_f32_e32 v157, v157
	v_rcp_f32_e32 v158, v158
	v_rcp_f32_e32 v159, v159
	v_rcp_f32_e32 v116, v116
	v_rcp_f32_e32 v117, v117
	v_rcp_f32_e32 v118, v118
	v_rcp_f32_e32 v119, v119
	v_rcp_f32_e32 v108, v108
	v_rcp_f32_e32 v109, v109
	v_rcp_f32_e32 v110, v110
	v_rcp_f32_e32 v111, v111
	v_rcp_f32_e32 v100, v100
	v_rcp_f32_e32 v101, v101
	v_rcp_f32_e32 v102, v102
	v_rcp_f32_e32 v103, v103
	v_pk_mul_f32 v[176:177], v[176:177], v[156:157]
	v_pk_mul_f32 v[178:179], v[178:179], v[158:159]
	v_pk_mul_f32 v[180:181], v[180:181], v[116:117]
	v_pk_mul_f32 v[182:183], v[182:183], v[118:119]
	v_pk_mul_f32 v[184:185], v[184:185], v[108:109]
	v_pk_mul_f32 v[186:187], v[186:187], v[110:111]
	v_pk_mul_f32 v[224:225], v[224:225], v[100:101]
	v_pk_mul_f32 v[226:227], v[226:227], v[102:103]
	v_pk_mul_f32 v[176:177], v[152:153], v[176:177]
	v_pk_mul_f32 v[178:179], v[154:155], v[178:179]
	v_pk_mul_f32 v[180:181], v[112:113], v[180:181]
	v_pk_mul_f32 v[182:183], v[114:115], v[182:183]
	v_pk_mul_f32 v[184:185], v[104:105], v[184:185]
	v_pk_mul_f32 v[186:187], v[106:107], v[186:187]
	v_pk_mul_f32 v[224:225], v[96:97], v[224:225]
	v_pk_mul_f32 v[226:227], v[98:99], v[226:227]
	v_cvt_pk_bf16_f32 v156, v176, v177
	v_cvt_pk_bf16_f32 v157, v178, v179
	v_cvt_pk_bf16_f32 v116, v180, v181
	v_cvt_pk_bf16_f32 v117, v182, v183
	v_cvt_pk_bf16_f32 v108, v184, v185
	v_cvt_pk_bf16_f32 v109, v186, v187
	v_cvt_pk_bf16_f32 v100, v224, v225
	v_cvt_pk_bf16_f32 v101, v226, v227
	s_waitcnt vmcnt(4)
	v_mov_b32_dpp v216, v32 row_shr:1 row_mask:0xf bank_mask:0xf bound_ctrl:1
	v_mov_b32_dpp v217, v33 row_shr:1 row_mask:0xf bank_mask:0xf bound_ctrl:1
	v_mov_b32_dpp v218, v34 row_shr:1 row_mask:0xf bank_mask:0xf bound_ctrl:1
	v_mov_b32_dpp v219, v35 row_shr:1 row_mask:0xf bank_mask:0xf bound_ctrl:1
	v_mov_b32_dpp v220, v56 row_shl:1 row_mask:0xf bank_mask:0xf bound_ctrl:1
	v_mov_b32_dpp v221, v57 row_shl:1 row_mask:0xf bank_mask:0xf bound_ctrl:1
	v_mov_b32_dpp v222, v58 row_shl:1 row_mask:0xf bank_mask:0xf bound_ctrl:1
	v_mov_b32_dpp v223, v59 row_shl:1 row_mask:0xf bank_mask:0xf bound_ctrl:1
	v_pk_mul_f32 v[176:177], v[56:57], v[132:133]
	v_pk_mul_f32 v[178:179], v[58:59], v[134:135]
	v_pk_mul_f32 v[180:181], v[48:49], v[132:133]
	v_pk_mul_f32 v[182:183], v[50:51], v[134:135]
	v_pk_mul_f32 v[184:185], v[40:41], v[132:133]
	v_pk_mul_f32 v[186:187], v[42:43], v[134:135]
	v_pk_mul_f32 v[224:225], v[32:33], v[132:133]
	v_pk_mul_f32 v[226:227], v[34:35], v[134:135]
	v_pk_fma_f32 v[176:177], v[128:129], v[216:217], v[176:177]
	v_pk_fma_f32 v[178:179], v[130:131], v[218:219], v[178:179]
	v_pk_fma_f32 v[180:181], v[128:129], v[56:57], v[180:181]
	v_pk_fma_f32 v[182:183], v[130:131], v[58:59], v[182:183]
	v_pk_fma_f32 v[184:185], v[128:129], v[48:49], v[184:185]
	v_pk_fma_f32 v[186:187], v[130:131], v[50:51], v[186:187]
	v_pk_fma_f32 v[224:225], v[128:129], v[40:41], v[224:225]
	v_pk_fma_f32 v[226:227], v[130:131], v[42:43], v[226:227]
	v_pk_fma_f32 v[176:177], v[136:137], v[48:49], v[176:177]
	v_pk_fma_f32 v[178:179], v[138:139], v[50:51], v[178:179]
	v_pk_fma_f32 v[180:181], v[136:137], v[40:41], v[180:181]
	v_pk_fma_f32 v[182:183], v[138:139], v[42:43], v[182:183]
	v_pk_fma_f32 v[184:185], v[136:137], v[32:33], v[184:185]
	v_pk_fma_f32 v[186:187], v[138:139], v[34:35], v[186:187]
	v_pk_fma_f32 v[224:225], v[136:137], v[220:221], v[224:225]
	v_pk_fma_f32 v[226:227], v[138:139], v[222:223], v[226:227]
	v_pk_add_f32 v[176:177], v[140:141], v[176:177]
	v_pk_add_f32 v[178:179], v[142:143], v[178:179]
	v_pk_add_f32 v[180:181], v[140:141], v[180:181]
	v_pk_add_f32 v[182:183], v[142:143], v[182:183]
	v_pk_add_f32 v[184:185], v[140:141], v[184:185]
	v_pk_add_f32 v[186:187], v[142:143], v[186:187]
	v_pk_add_f32 v[224:225], v[140:141], v[224:225]
	v_pk_add_f32 v[226:227], v[142:143], v[226:227]
	s_waitcnt vmcnt(0)
; __device__ __forceinline__ void st_bf4(bf16_t* p, f32x4 v) { u32x2 w; w.x = pk2(v[0], v[1]); w.y = pk2(v[2], v[3]); *(u32x2*)p = w; }
; __device__ __forceinline__ float sigmoidf_(float x) { return __builtin_amdgcn_rcpf(1.f + __expf(-x)); }
; __device__ __forceinline__ float dpp_ror1(float v) { return __int_as_float(__builtin_amdgcn_update_dpp(0, __float_as_int(v), 0x121, 0xf, 0xf, false)); }
; __device__ __forceinline__ float dpp_rol1(float v) { return __int_as_float(__builtin_amdgcn_update_dpp(0, __float_as_int(v), 0x12F, 0xf, 0xf, false)); }
;     __device__ __forceinline__ void tile(const f32x4 (&acc)[2][2][4][2], const Unit& u, int wr, int wc, int fr, int fq) const {
;     ...
;                     for (int i = 0; i < 4; ++i) {
;                         const float xv = acc[ai][0][m][n][i], xg = acc[ai][1][m][n][i];
;                         const float uv = m > 0 ? acc[ai][0][m > 0 ? m - 1 : 0][n][i] : 0.f, ug = m > 0 ? acc[ai][1][m > 0 ? m - 1 : 0][n][i] : 0.f;
;                         const float dv = m < 3 ? acc[ai][0][m < 3 ? m + 1 : 3][n][i] : 0.f, dg = m < 3 ? acc[ai][1][m < 3 ? m + 1 : 3][n][i] : 0.f;
;                         const float pv = dpp_ror1(fr == 15 ? uv : xv), pg = dpp_ror1(fr == 15 ? ug : xg);
;                         const float nv = dpp_rol1(fr == 0 ? dv : xv), ng = dpp_rol1(fr == 0 ? dg : xg);
;                         const float yv = wv0[i] * pv + wv1[i] * xv + wv2[i] * nv + bv[i];
;                         const float yg = wg0[i] * pg + wg1[i] * xg + wg2[i] * ng + bg[i];
;                         r[i] = yg * sigmoidf_(yg) * yv;
;                     }
;                     st_bf4(ACT + (size_t)(u.pm * BM + ai * HALF + wr * 64 + m * 16 + fr) * FF + cv, r);
	v_mov_b32_dpp v216, v36 row_shr:1 row_mask:0xf bank_mask:0xf bound_ctrl:1
	v_mov_b32_dpp v217, v37 row_shr:1 row_mask:0xf bank_mask:0xf bound_ctrl:1
	v_mov_b32_dpp v218, v38 row_shr:1 row_mask:0xf bank_mask:0xf bound_ctrl:1
	v_mov_b32_dpp v219, v39 row_shr:1 row_mask:0xf bank_mask:0xf bound_ctrl:1
	v_mov_b32_dpp v220, v60 row_shl:1 row_mask:0xf bank_mask:0xf bound_ctrl:1
	v_mov_b32_dpp v221, v61 row_shl:1 row_mask:0xf bank_mask:0xf bound_ctrl:1
	v_mov_b32_dpp v222, v62 row_shl:1 row_mask:0xf bank_mask:0xf bound_ctrl:1
	v_mov_b32_dpp v223, v63 row_shl:1 row_mask:0xf bank_mask:0xf bound_ctrl:1
	v_pk_mul_f32 v[56:57], v[60:61], v[148:149]
	v_pk_mul_f32 v[58:59], v[62:63], v[150:151]
	v_pk_mul_f32 v[48:49], v[52:53], v[148:149]
	v_pk_mul_f32 v[50:51], v[54:55], v[150:151]
	v_pk_mul_f32 v[40:41], v[44:45], v[148:149]
	v_pk_mul_f32 v[42:43], v[46:47], v[150:151]
	v_pk_mul_f32 v[32:33], v[36:37], v[148:149]
	v_pk_mul_f32 v[34:35], v[38:39], v[150:151]
	v_pk_fma_f32 v[56:57], v[144:145], v[216:217], v[56:57]
	v_pk_fma_f32 v[58:59], v[146:147], v[218:219], v[58:59]
	v_pk_fma_f32 v[48:49], v[144:145], v[60:61], v[48:49]
	v_pk_fma_f32 v[50:51], v[146:147], v[62:63], v[50:51]
	v_pk_fma_f32 v[40:41], v[144:145], v[52:53], v[40:41]
	v_pk_fma_f32 v[42:43], v[146:147], v[54:55], v[42:43]
	v_pk_fma_f32 v[32:33], v[144:145], v[44:45], v[32:33]
	v_pk_fma_f32 v[34:35], v[146:147], v[46:47], v[34:35]
	v_pk_fma_f32 v[56:57], v[208:209], v[52:53], v[56:57]
	v_pk_fma_f32 v[58:59], v[210:211], v[54:55], v[58:59]
	v_pk_fma_f32 v[48:49], v[208:209], v[44:45], v[48:49]
	v_pk_fma_f32 v[50:51], v[210:211], v[46:47], v[50:51]
	v_pk_fma_f32 v[40:41], v[208:209], v[36:37], v[40:41]
	v_pk_fma_f32 v[42:43], v[210:211], v[38:39], v[42:43]
	v_pk_fma_f32 v[32:33], v[208:209], v[220:221], v[32:33]
	v_pk_fma_f32 v[34:35], v[210:211], v[222:223], v[34:35]
	v_pk_add_f32 v[56:57], v[212:213], v[56:57]
	v_pk_add_f32 v[58:59], v[214:215], v[58:59]
	v_pk_add_f32 v[48:49], v[212:213], v[48:49]
	v_pk_add_f32 v[50:51], v[214:215], v[50:51]
	v_pk_add_f32 v[40:41], v[212:213], v[40:41]
	v_pk_add_f32 v[42:43], v[214:215], v[42:43]
	v_pk_add_f32 v[32:33], v[212:213], v[32:33]
	v_pk_add_f32 v[34:35], v[214:215], v[34:35]
	v_mul_f32_e32 v60, 0xbfb8aa3b, v176
	v_mul_f32_e32 v61, 0xbfb8aa3b, v177
	v_mul_f32_e32 v62, 0xbfb8aa3b, v178
	v_mul_f32_e32 v63, 0xbfb8aa3b, v179
	v_mul_f32_e32 v52, 0xbfb8aa3b, v180
	v_mul_f32_e32 v53, 0xbfb8aa3b, v181
	v_mul_f32_e32 v54, 0xbfb8aa3b, v182
	v_mul_f32_e32 v55, 0xbfb8aa3b, v183
	v_mul_f32_e32 v44, 0xbfb8aa3b, v184
	v_mul_f32_e32 v45, 0xbfb8aa3b, v185
	v_mul_f32_e32 v46, 0xbfb8aa3b, v186
	v_mul_f32_e32 v47, 0xbfb8aa3b, v187
	v_mul_f32_e32 v36, 0xbfb8aa3b, v224
	v_mul_f32_e32 v37, 0xbfb8aa3b, v225
	v_mul_f32_e32 v38, 0xbfb8aa3b, v226
	v_mul_f32_e32 v39, 0xbfb8aa3b, v227
	v_exp_f32_e32 v60, v60
	v_exp_f32_e32 v61, v61
	v_exp_f32_e32 v62, v62
	v_exp_f32_e32 v63, v63
	v_exp_f32_e32 v52, v52
	v_exp_f32_e32 v53, v53
	v_exp_f32_e32 v54, v54
	v_exp_f32_e32 v55, v55
	v_exp_f32_e32 v44, v44
	v_exp_f32_e32 v45, v45
	v_exp_f32_e32 v46, v46
	v_exp_f32_e32 v47, v47
	v_exp_f32_e32 v36, v36
	v_exp_f32_e32 v37, v37
	v_exp_f32_e32 v38, v38
	v_exp_f32_e32 v39, v39
	v_add_f32_e32 v60, 1.0, v60
	v_add_f32_e32 v61, 1.0, v61
	v_add_f32_e32 v62, 1.0, v62
	v_add_f32_e32 v63, 1.0, v63
	v_add_f32_e32 v52, 1.0, v52
	v_add_f32_e32 v53, 1.0, v53
	v_add_f32_e32 v54, 1.0, v54
	v_add_f32_e32 v55, 1.0, v55
	v_add_f32_e32 v44, 1.0, v44
	v_add_f32_e32 v45, 1.0, v45
	v_add_f32_e32 v46, 1.0, v46
	v_add_f32_e32 v47, 1.0, v47
	v_add_f32_e32 v36, 1.0, v36
	v_add_f32_e32 v37, 1.0, v37
	v_add_f32_e32 v38, 1.0, v38
	v_add_f32_e32 v39, 1.0, v39
	v_rcp_f32_e32 v60, v60
	v_rcp_f32_e32 v61, v61
	v_rcp_f32_e32 v62, v62
	v_rcp_f32_e32 v63, v63
	v_rcp_f32_e32 v52, v52
	v_rcp_f32_e32 v53, v53
	v_rcp_f32_e32 v54, v54
	v_rcp_f32_e32 v55, v55
	v_rcp_f32_e32 v44, v44
	v_rcp_f32_e32 v45, v45
	v_rcp_f32_e32 v46, v46
	v_rcp_f32_e32 v47, v47
	v_rcp_f32_e32 v36, v36
	v_rcp_f32_e32 v37, v37
	v_rcp_f32_e32 v38, v38
	v_rcp_f32_e32 v39, v39
	v_pk_mul_f32 v[176:177], v[176:177], v[60:61]
	v_pk_mul_f32 v[178:179], v[178:179], v[62:63]
	v_pk_mul_f32 v[180:181], v[180:181], v[52:53]
	v_pk_mul_f32 v[182:183], v[182:183], v[54:55]
	v_pk_mul_f32 v[184:185], v[184:185], v[44:45]
	v_pk_mul_f32 v[186:187], v[186:187], v[46:47]
	v_pk_mul_f32 v[224:225], v[224:225], v[36:37]
	v_pk_mul_f32 v[226:227], v[226:227], v[38:39]
	v_pk_mul_f32 v[176:177], v[56:57], v[176:177]
	v_pk_mul_f32 v[178:179], v[58:59], v[178:179]
	v_pk_mul_f32 v[180:181], v[48:49], v[180:181]
	v_pk_mul_f32 v[182:183], v[50:51], v[182:183]
	v_pk_mul_f32 v[184:185], v[40:41], v[184:185]
	v_pk_mul_f32 v[186:187], v[42:43], v[186:187]
	v_pk_mul_f32 v[224:225], v[32:33], v[224:225]
	v_pk_mul_f32 v[226:227], v[34:35], v[226:227]
	v_cvt_pk_bf16_f32 v158, v176, v177
	v_cvt_pk_bf16_f32 v159, v178, v179
	v_cvt_pk_bf16_f32 v118, v180, v181
	v_cvt_pk_bf16_f32 v119, v182, v183
	v_cvt_pk_bf16_f32 v110, v184, v185
	v_cvt_pk_bf16_f32 v111, v186, v187
	v_cvt_pk_bf16_f32 v102, v224, v225
	v_cvt_pk_bf16_f32 v103, v226, v227
	s_nop 1
	v_permlane16_swap_b32_e32 v156, v158
	v_permlane16_swap_b32_e32 v157, v159
	v_permlane16_swap_b32_e32 v116, v118
	v_permlane16_swap_b32_e32 v117, v119
	v_permlane16_swap_b32_e32 v108, v110
	v_permlane16_swap_b32_e32 v109, v111
	v_permlane16_swap_b32_e32 v100, v102
	v_permlane16_swap_b32_e32 v101, v103
	global_store_dwordx4 v173, v[156:159], s[0:1]
	v_add_u32_e32 v175, 0x2c00, v173
	global_store_dwordx4 v175, v[116:119], s[0:1]
	v_add_u32_e32 v175, 0x5800, v173
	global_store_dwordx4 v175, v[108:111], s[0:1]
	v_add_u32_e32 v175, 0x8400, v173
; __device__ __forceinline__ float sigmoidf_(float x) { return __builtin_amdgcn_rcpf(1.f + __expf(-x)); }
; __device__ __forceinline__ float dpp_ror1(float v) { return __int_as_float(__builtin_amdgcn_update_dpp(0, __float_as_int(v), 0x121, 0xf, 0xf, false)); }
; __device__ __forceinline__ float dpp_rol1(float v) { return __int_as_float(__builtin_amdgcn_update_dpp(0, __float_as_int(v), 0x12F, 0xf, 0xf, false)); }
;     __device__ __forceinline__ void tile(const f32x4 (&acc)[2][2][4][2], const Unit& u, int wr, int wc, int fr, int fq) const {
;     ...
;                     for (int i = 0; i < 4; ++i) {
;                         const float xv = acc[ai][0][m][n][i], xg = acc[ai][1][m][n][i];
;                         const float uv = m > 0 ? acc[ai][0][m > 0 ? m - 1 : 0][n][i] : 0.f, ug = m > 0 ? acc[ai][1][m > 0 ? m - 1 : 0][n][i] : 0.f;
;                         const float dv = m < 3 ? acc[ai][0][m < 3 ? m + 1 : 3][n][i] : 0.f, dg = m < 3 ? acc[ai][1][m < 3 ? m + 1 : 3][n][i] : 0.f;
;                         const float pv = dpp_ror1(fr == 15 ? uv : xv), pg = dpp_ror1(fr == 15 ? ug : xg);
;                         const float nv = dpp_rol1(fr == 0 ? dv : xv), ng = dpp_rol1(fr == 0 ? dg : xg);
;                         const float yv = wv0[i] * pv + wv1[i] * xv + wv2[i] * nv + bv[i];
;                         const float yg = wg0[i] * pg + wg1[i] * xg + wg2[i] * ng + bg[i];
;                         r[i] = yg * sigmoidf_(yg) * yv;
	global_store_dwordx4 v175, v[100:103], s[0:1]
	v_mov_b32_dpp v216, v64 row_shr:1 row_mask:0xf bank_mask:0xf bound_ctrl:1
	v_mov_b32_dpp v217, v65 row_shr:1 row_mask:0xf bank_mask:0xf bound_ctrl:1
	v_mov_b32_dpp v218, v66 row_shr:1 row_mask:0xf bank_mask:0xf bound_ctrl:1
	v_mov_b32_dpp v219, v67 row_shr:1 row_mask:0xf bank_mask:0xf bound_ctrl:1
	v_mov_b32_dpp v220, v88 row_shl:1 row_mask:0xf bank_mask:0xf bound_ctrl:1
	v_mov_b32_dpp v221, v89 row_shl:1 row_mask:0xf bank_mask:0xf bound_ctrl:1
	v_mov_b32_dpp v222, v90 row_shl:1 row_mask:0xf bank_mask:0xf bound_ctrl:1
	v_mov_b32_dpp v223, v91 row_shl:1 row_mask:0xf bank_mask:0xf bound_ctrl:1
	v_pk_mul_f32 v[176:177], v[88:89], v[234:235]
	v_pk_mul_f32 v[178:179], v[90:91], v[236:237]
	v_pk_mul_f32 v[180:181], v[80:81], v[234:235]
	v_pk_mul_f32 v[182:183], v[82:83], v[236:237]
	v_pk_mul_f32 v[184:185], v[72:73], v[234:235]
	v_pk_mul_f32 v[186:187], v[74:75], v[236:237]
	v_pk_mul_f32 v[224:225], v[64:65], v[234:235]
	v_pk_mul_f32 v[226:227], v[66:67], v[236:237]
	v_pk_fma_f32 v[176:177], v[230:231], v[216:217], v[176:177]
	v_pk_fma_f32 v[178:179], v[232:233], v[218:219], v[178:179]
	v_pk_fma_f32 v[180:181], v[230:231], v[88:89], v[180:181]
	v_pk_fma_f32 v[182:183], v[232:233], v[90:91], v[182:183]
	v_pk_fma_f32 v[184:185], v[230:231], v[80:81], v[184:185]
	v_pk_fma_f32 v[186:187], v[232:233], v[82:83], v[186:187]
	v_pk_fma_f32 v[224:225], v[230:231], v[72:73], v[224:225]
	v_pk_fma_f32 v[226:227], v[232:233], v[74:75], v[226:227]
	v_pk_fma_f32 v[176:177], v[238:239], v[80:81], v[176:177]
	v_pk_fma_f32 v[178:179], v[240:241], v[82:83], v[178:179]
	v_pk_fma_f32 v[180:181], v[238:239], v[72:73], v[180:181]
	v_pk_fma_f32 v[182:183], v[240:241], v[74:75], v[182:183]
	v_pk_fma_f32 v[184:185], v[238:239], v[64:65], v[184:185]
	v_pk_fma_f32 v[186:187], v[240:241], v[66:67], v[186:187]
	v_pk_fma_f32 v[224:225], v[238:239], v[220:221], v[224:225]
	v_pk_fma_f32 v[226:227], v[240:241], v[222:223], v[226:227]
	v_pk_add_f32 v[176:177], v[242:243], v[176:177]
	v_pk_add_f32 v[178:179], v[244:245], v[178:179]
	v_pk_add_f32 v[180:181], v[242:243], v[180:181]
	v_pk_add_f32 v[182:183], v[244:245], v[182:183]
	v_pk_add_f32 v[184:185], v[242:243], v[184:185]
	v_pk_add_f32 v[186:187], v[244:245], v[186:187]
	v_pk_add_f32 v[224:225], v[242:243], v[224:225]
	v_pk_add_f32 v[226:227], v[244:245], v[226:227]
	v_mov_b32_dpp v216, v68 row_shr:1 row_mask:0xf bank_mask:0xf bound_ctrl:1
	v_mov_b32_dpp v217, v69 row_shr:1 row_mask:0xf bank_mask:0xf bound_ctrl:1
	v_mov_b32_dpp v218, v70 row_shr:1 row_mask:0xf bank_mask:0xf bound_ctrl:1
	v_mov_b32_dpp v219, v71 row_shr:1 row_mask:0xf bank_mask:0xf bound_ctrl:1
	v_mov_b32_dpp v220, v92 row_shl:1 row_mask:0xf bank_mask:0xf bound_ctrl:1
	v_mov_b32_dpp v221, v93 row_shl:1 row_mask:0xf bank_mask:0xf bound_ctrl:1
	v_mov_b32_dpp v222, v94 row_shl:1 row_mask:0xf bank_mask:0xf bound_ctrl:1
	v_mov_b32_dpp v223, v95 row_shl:1 row_mask:0xf bank_mask:0xf bound_ctrl:1
	v_pk_mul_f32 v[88:89], v[92:93], v[250:251]
	v_pk_mul_f32 v[90:91], v[94:95], v[252:253]
	v_pk_mul_f32 v[80:81], v[84:85], v[250:251]
	v_pk_mul_f32 v[82:83], v[86:87], v[252:253]
	v_pk_mul_f32 v[72:73], v[76:77], v[250:251]
	v_pk_mul_f32 v[74:75], v[78:79], v[252:253]
	v_pk_mul_f32 v[64:65], v[68:69], v[250:251]
	v_pk_mul_f32 v[66:67], v[70:71], v[252:253]
	v_pk_fma_f32 v[88:89], v[246:247], v[216:217], v[88:89]
	v_pk_fma_f32 v[90:91], v[248:249], v[218:219], v[90:91]
	v_pk_fma_f32 v[80:81], v[246:247], v[92:93], v[80:81]
	v_pk_fma_f32 v[82:83], v[248:249], v[94:95], v[82:83]
	v_pk_fma_f32 v[72:73], v[246:247], v[84:85], v[72:73]
	v_pk_fma_f32 v[74:75], v[248:249], v[86:87], v[74:75]
	v_pk_fma_f32 v[64:65], v[246:247], v[76:77], v[64:65]
	v_pk_fma_f32 v[66:67], v[248:249], v[78:79], v[66:67]
	v_pk_fma_f32 v[88:89], v[120:121], v[84:85], v[88:89]
	v_pk_fma_f32 v[90:91], v[122:123], v[86:87], v[90:91]
	v_pk_fma_f32 v[80:81], v[120:121], v[76:77], v[80:81]
	v_pk_fma_f32 v[82:83], v[122:123], v[78:79], v[82:83]
	v_pk_fma_f32 v[72:73], v[120:121], v[68:69], v[72:73]
	v_pk_fma_f32 v[74:75], v[122:123], v[70:71], v[74:75]
	v_pk_fma_f32 v[64:65], v[120:121], v[220:221], v[64:65]
	v_pk_fma_f32 v[66:67], v[122:123], v[222:223], v[66:67]
	v_pk_add_f32 v[88:89], v[124:125], v[88:89]
	v_pk_add_f32 v[90:91], v[126:127], v[90:91]
	v_pk_add_f32 v[80:81], v[124:125], v[80:81]
	v_pk_add_f32 v[82:83], v[126:127], v[82:83]
	v_pk_add_f32 v[72:73], v[124:125], v[72:73]
	v_pk_add_f32 v[74:75], v[126:127], v[74:75]
	v_pk_add_f32 v[64:65], v[124:125], v[64:65]
	v_pk_add_f32 v[66:67], v[126:127], v[66:67]
	v_mul_f32_e32 v92, 0xbfb8aa3b, v176
	v_mul_f32_e32 v93, 0xbfb8aa3b, v177
	v_mul_f32_e32 v94, 0xbfb8aa3b, v178
	v_mul_f32_e32 v95, 0xbfb8aa3b, v179
	v_mul_f32_e32 v84, 0xbfb8aa3b, v180
	v_mul_f32_e32 v85, 0xbfb8aa3b, v181
	v_mul_f32_e32 v86, 0xbfb8aa3b, v182
	v_mul_f32_e32 v87, 0xbfb8aa3b, v183
	v_mul_f32_e32 v76, 0xbfb8aa3b, v184
	v_mul_f32_e32 v77, 0xbfb8aa3b, v185
	v_mul_f32_e32 v78, 0xbfb8aa3b, v186
	v_mul_f32_e32 v79, 0xbfb8aa3b, v187
	v_mul_f32_e32 v68, 0xbfb8aa3b, v224
	v_mul_f32_e32 v69, 0xbfb8aa3b, v225
	v_mul_f32_e32 v70, 0xbfb8aa3b, v226
	v_mul_f32_e32 v71, 0xbfb8aa3b, v227
	v_exp_f32_e32 v92, v92
	v_exp_f32_e32 v93, v93
	v_exp_f32_e32 v94, v94
	v_exp_f32_e32 v95, v95
	v_exp_f32_e32 v84, v84
	v_exp_f32_e32 v85, v85
	v_exp_f32_e32 v86, v86
	v_exp_f32_e32 v87, v87
	v_exp_f32_e32 v76, v76
	v_exp_f32_e32 v77, v77
	v_exp_f32_e32 v78, v78
	v_exp_f32_e32 v79, v79
	v_exp_f32_e32 v68, v68
	v_exp_f32_e32 v69, v69
	v_exp_f32_e32 v70, v70
	v_exp_f32_e32 v71, v71
	v_add_f32_e32 v92, 1.0, v92
	v_add_f32_e32 v93, 1.0, v93
	v_add_f32_e32 v94, 1.0, v94
; __device__ __forceinline__ void st_bf4(bf16_t* p, f32x4 v) { u32x2 w; w.x = pk2(v[0], v[1]); w.y = pk2(v[2], v[3]); *(u32x2*)p = w; }
; __device__ __forceinline__ float sigmoidf_(float x) { return __builtin_amdgcn_rcpf(1.f + __expf(-x)); }
; __device__ __forceinline__ float dpp_ror1(float v) { return __int_as_float(__builtin_amdgcn_update_dpp(0, __float_as_int(v), 0x121, 0xf, 0xf, false)); }
; __device__ __forceinline__ float dpp_rol1(float v) { return __int_as_float(__builtin_amdgcn_update_dpp(0, __float_as_int(v), 0x12F, 0xf, 0xf, false)); }
;     __device__ __forceinline__ void tile(const f32x4 (&acc)[2][2][4][2], const Unit& u, int wr, int wc, int fr, int fq) const {
;     ...
;                         const float xv = acc[ai][0][m][n][i], xg = acc[ai][1][m][n][i];
;                         const float uv = m > 0 ? acc[ai][0][m > 0 ? m - 1 : 0][n][i] : 0.f, ug = m > 0 ? acc[ai][1][m > 0 ? m - 1 : 0][n][i] : 0.f;
;                         const float dv = m < 3 ? acc[ai][0][m < 3 ? m + 1 : 3][n][i] : 0.f, dg = m < 3 ? acc[ai][1][m < 3 ? m + 1 : 3][n][i] : 0.f;
;                         const float pv = dpp_ror1(fr == 15 ? uv : xv), pg = dpp_ror1(fr == 15 ? ug : xg);
;                         const float nv = dpp_rol1(fr == 0 ? dv : xv), ng = dpp_rol1(fr == 0 ? dg : xg);
;                         const float yv = wv0[i] * pv + wv1[i] * xv + wv2[i] * nv + bv[i];
;                         const float yg = wg0[i] * pg + wg1[i] * xg + wg2[i] * ng + bg[i];
;                         r[i] = yg * sigmoidf_(yg) * yv;
;                     }
;                     st_bf4(ACT + (size_t)(u.pm * BM + ai * HALF + wr * 64 + m * 16 + fr) * FF + cv, r);
;                 }
	v_add_f32_e32 v95, 1.0, v95
	v_add_f32_e32 v84, 1.0, v84
	v_add_f32_e32 v85, 1.0, v85
	v_add_f32_e32 v86, 1.0, v86
	v_add_f32_e32 v87, 1.0, v87
	v_add_f32_e32 v76, 1.0, v76
	v_add_f32_e32 v77, 1.0, v77
	v_add_f32_e32 v78, 1.0, v78
	v_add_f32_e32 v79, 1.0, v79
	v_add_f32_e32 v68, 1.0, v68
	v_add_f32_e32 v69, 1.0, v69
	v_add_f32_e32 v70, 1.0, v70
	v_add_f32_e32 v71, 1.0, v71
	v_rcp_f32_e32 v92, v92
	v_rcp_f32_e32 v93, v93
	v_rcp_f32_e32 v94, v94
	v_rcp_f32_e32 v95, v95
	v_rcp_f32_e32 v84, v84
	v_rcp_f32_e32 v85, v85
	v_rcp_f32_e32 v86, v86
	v_rcp_f32_e32 v87, v87
	v_rcp_f32_e32 v76, v76
	v_rcp_f32_e32 v77, v77
	v_rcp_f32_e32 v78, v78
	v_rcp_f32_e32 v79, v79
	v_rcp_f32_e32 v68, v68
	v_rcp_f32_e32 v69, v69
	v_rcp_f32_e32 v70, v70
	v_rcp_f32_e32 v71, v71
	v_pk_mul_f32 v[176:177], v[176:177], v[92:93]
	v_pk_mul_f32 v[178:179], v[178:179], v[94:95]
	v_pk_mul_f32 v[180:181], v[180:181], v[84:85]
	v_pk_mul_f32 v[182:183], v[182:183], v[86:87]
	v_pk_mul_f32 v[184:185], v[184:185], v[76:77]
	v_pk_mul_f32 v[186:187], v[186:187], v[78:79]
	v_pk_mul_f32 v[224:225], v[224:225], v[68:69]
	v_pk_mul_f32 v[226:227], v[226:227], v[70:71]
	v_pk_mul_f32 v[176:177], v[88:89], v[176:177]
	v_pk_mul_f32 v[178:179], v[90:91], v[178:179]
	v_pk_mul_f32 v[180:181], v[80:81], v[180:181]
	v_pk_mul_f32 v[182:183], v[82:83], v[182:183]
	v_pk_mul_f32 v[184:185], v[72:73], v[184:185]
	v_pk_mul_f32 v[186:187], v[74:75], v[186:187]
	v_pk_mul_f32 v[224:225], v[64:65], v[224:225]
	v_pk_mul_f32 v[226:227], v[66:67], v[226:227]
	v_cvt_pk_bf16_f32 v92, v176, v177
	v_cvt_pk_bf16_f32 v93, v178, v179
	v_cvt_pk_bf16_f32 v84, v180, v181
	v_cvt_pk_bf16_f32 v85, v182, v183
	v_cvt_pk_bf16_f32 v76, v184, v185
	v_cvt_pk_bf16_f32 v77, v186, v187
	v_cvt_pk_bf16_f32 v68, v224, v225
	v_cvt_pk_bf16_f32 v69, v226, v227
	v_mov_b32_dpp v216, v0 row_shr:1 row_mask:0xf bank_mask:0xf bound_ctrl:1
	v_mov_b32_dpp v217, v1 row_shr:1 row_mask:0xf bank_mask:0xf bound_ctrl:1
	v_mov_b32_dpp v218, v2 row_shr:1 row_mask:0xf bank_mask:0xf bound_ctrl:1
	v_mov_b32_dpp v219, v3 row_shr:1 row_mask:0xf bank_mask:0xf bound_ctrl:1
	v_mov_b32_dpp v220, v24 row_shl:1 row_mask:0xf bank_mask:0xf bound_ctrl:1
	v_mov_b32_dpp v221, v25 row_shl:1 row_mask:0xf bank_mask:0xf bound_ctrl:1
	v_mov_b32_dpp v222, v26 row_shl:1 row_mask:0xf bank_mask:0xf bound_ctrl:1
	v_mov_b32_dpp v223, v27 row_shl:1 row_mask:0xf bank_mask:0xf bound_ctrl:1
	v_pk_mul_f32 v[176:177], v[24:25], v[132:133]
	v_pk_mul_f32 v[178:179], v[26:27], v[134:135]
	v_pk_mul_f32 v[180:181], v[16:17], v[132:133]
	v_pk_mul_f32 v[182:183], v[18:19], v[134:135]
	v_pk_mul_f32 v[184:185], v[8:9], v[132:133]
	v_pk_mul_f32 v[186:187], v[10:11], v[134:135]
	v_pk_mul_f32 v[224:225], v[0:1], v[132:133]
	v_pk_mul_f32 v[226:227], v[2:3], v[134:135]
	v_pk_fma_f32 v[176:177], v[128:129], v[216:217], v[176:177]
	v_pk_fma_f32 v[178:179], v[130:131], v[218:219], v[178:179]
	v_pk_fma_f32 v[180:181], v[128:129], v[24:25], v[180:181]
	v_pk_fma_f32 v[182:183], v[130:131], v[26:27], v[182:183]
	v_pk_fma_f32 v[184:185], v[128:129], v[16:17], v[184:185]
	v_pk_fma_f32 v[186:187], v[130:131], v[18:19], v[186:187]
	v_pk_fma_f32 v[224:225], v[128:129], v[8:9], v[224:225]
	v_pk_fma_f32 v[226:227], v[130:131], v[10:11], v[226:227]
	v_pk_fma_f32 v[176:177], v[136:137], v[16:17], v[176:177]
	v_pk_fma_f32 v[178:179], v[138:139], v[18:19], v[178:179]
	v_pk_fma_f32 v[180:181], v[136:137], v[8:9], v[180:181]
	v_pk_fma_f32 v[182:183], v[138:139], v[10:11], v[182:183]
	v_pk_fma_f32 v[184:185], v[136:137], v[0:1], v[184:185]
	v_pk_fma_f32 v[186:187], v[138:139], v[2:3], v[186:187]
	v_pk_fma_f32 v[224:225], v[136:137], v[220:221], v[224:225]
	v_pk_fma_f32 v[226:227], v[138:139], v[222:223], v[226:227]
	v_pk_add_f32 v[176:177], v[140:141], v[176:177]
	v_pk_add_f32 v[178:179], v[142:143], v[178:179]
	v_pk_add_f32 v[180:181], v[140:141], v[180:181]
	v_pk_add_f32 v[182:183], v[142:143], v[182:183]
	v_pk_add_f32 v[184:185], v[140:141], v[184:185]
	v_pk_add_f32 v[186:187], v[142:143], v[186:187]
	v_pk_add_f32 v[224:225], v[140:141], v[224:225]
	v_pk_add_f32 v[226:227], v[142:143], v[226:227]
	v_mov_b32_dpp v216, v4 row_shr:1 row_mask:0xf bank_mask:0xf bound_ctrl:1
	v_mov_b32_dpp v217, v5 row_shr:1 row_mask:0xf bank_mask:0xf bound_ctrl:1
	v_mov_b32_dpp v218, v6 row_shr:1 row_mask:0xf bank_mask:0xf bound_ctrl:1
	v_mov_b32_dpp v219, v7 row_shr:1 row_mask:0xf bank_mask:0xf bound_ctrl:1
	v_mov_b32_dpp v220, v28 row_shl:1 row_mask:0xf bank_mask:0xf bound_ctrl:1
	v_mov_b32_dpp v221, v29 row_shl:1 row_mask:0xf bank_mask:0xf bound_ctrl:1
	v_mov_b32_dpp v222, v30 row_shl:1 row_mask:0xf bank_mask:0xf bound_ctrl:1
	v_mov_b32_dpp v223, v31 row_shl:1 row_mask:0xf bank_mask:0xf bound_ctrl:1
	v_pk_mul_f32 v[24:25], v[28:29], v[148:149]
	v_pk_mul_f32 v[26:27], v[30:31], v[150:151]
	v_pk_mul_f32 v[16:17], v[20:21], v[148:149]
	v_pk_mul_f32 v[18:19], v[22:23], v[150:151]
	v_pk_mul_f32 v[8:9], v[12:13], v[148:149]
	v_pk_mul_f32 v[10:11], v[14:15], v[150:151]
	v_pk_mul_f32 v[0:1], v[4:5], v[148:149]
	v_pk_mul_f32 v[2:3], v[6:7], v[150:151]
	v_pk_fma_f32 v[24:25], v[144:145], v[216:217], v[24:25]
; __device__ __forceinline__ void st_bf4(bf16_t* p, f32x4 v) { u32x2 w; w.x = pk2(v[0], v[1]); w.y = pk2(v[2], v[3]); *(u32x2*)p = w; }
; __device__ __forceinline__ float sigmoidf_(float x) { return __builtin_amdgcn_rcpf(1.f + __expf(-x)); }
; __device__ __forceinline__ float dpp_ror1(float v) { return __int_as_float(__builtin_amdgcn_update_dpp(0, __float_as_int(v), 0x121, 0xf, 0xf, false)); }
; __device__ __forceinline__ float dpp_rol1(float v) { return __int_as_float(__builtin_amdgcn_update_dpp(0, __float_as_int(v), 0x12F, 0xf, 0xf, false)); }
;     __device__ __forceinline__ void tile(const f32x4 (&acc)[2][2][4][2], const Unit& u, int wr, int wc, int fr, int fq) const {
;     ...
;             const f32x4 wv0 = *(const f32x4*)(cw + cv), wv1 = *(const f32x4*)(cw + F2 + cv), wv2 = *(const f32x4*)(cw + 2 * F2 + cv), bv = *(const f32x4*)(cb + cv);
;             const f32x4 wg0 = *(const f32x4*)(cw + cg), wg1 = *(const f32x4*)(cw + F2 + cg), wg2 = *(const f32x4*)(cw + 2 * F2 + cg), bg = *(const f32x4*)(cb + cg);
;     ...
;                         const float xv = acc[ai][0][m][n][i], xg = acc[ai][1][m][n][i];
;                         const float uv = m > 0 ? acc[ai][0][m > 0 ? m - 1 : 0][n][i] : 0.f, ug = m > 0 ? acc[ai][1][m > 0 ? m - 1 : 0][n][i] : 0.f;
;                         const float dv = m < 3 ? acc[ai][0][m < 3 ? m + 1 : 3][n][i] : 0.f, dg = m < 3 ? acc[ai][1][m < 3 ? m + 1 : 3][n][i] : 0.f;
;                         const float pv = dpp_ror1(fr == 15 ? uv : xv), pg = dpp_ror1(fr == 15 ? ug : xg);
;                         const float nv = dpp_rol1(fr == 0 ? dv : xv), ng = dpp_rol1(fr == 0 ? dg : xg);
;                         const float yv = wv0[i] * pv + wv1[i] * xv + wv2[i] * nv + bv[i];
;                         const float yg = wg0[i] * pg + wg1[i] * xg + wg2[i] * ng + bg[i];
;                         r[i] = yg * sigmoidf_(yg) * yv;
;                     }
;                     st_bf4(ACT + (size_t)(u.pm * BM + ai * HALF + wr * 64 + m * 16 + fr) * FF + cv, r);
;                 }
	v_pk_fma_f32 v[26:27], v[146:147], v[218:219], v[26:27]
	v_pk_fma_f32 v[16:17], v[144:145], v[28:29], v[16:17]
	v_pk_fma_f32 v[18:19], v[146:147], v[30:31], v[18:19]
	v_pk_fma_f32 v[8:9], v[144:145], v[20:21], v[8:9]
	v_pk_fma_f32 v[10:11], v[146:147], v[22:23], v[10:11]
	v_pk_fma_f32 v[0:1], v[144:145], v[12:13], v[0:1]
	v_pk_fma_f32 v[2:3], v[146:147], v[14:15], v[2:3]
	v_pk_fma_f32 v[24:25], v[208:209], v[20:21], v[24:25]
	v_pk_fma_f32 v[26:27], v[210:211], v[22:23], v[26:27]
	v_pk_fma_f32 v[16:17], v[208:209], v[12:13], v[16:17]
	v_pk_fma_f32 v[18:19], v[210:211], v[14:15], v[18:19]
	v_pk_fma_f32 v[8:9], v[208:209], v[4:5], v[8:9]
	v_pk_fma_f32 v[10:11], v[210:211], v[6:7], v[10:11]
	v_pk_fma_f32 v[0:1], v[208:209], v[220:221], v[0:1]
	v_pk_fma_f32 v[2:3], v[210:211], v[222:223], v[2:3]
	v_pk_add_f32 v[24:25], v[212:213], v[24:25]
	v_pk_add_f32 v[26:27], v[214:215], v[26:27]
	v_pk_add_f32 v[16:17], v[212:213], v[16:17]
	v_pk_add_f32 v[18:19], v[214:215], v[18:19]
	v_pk_add_f32 v[8:9], v[212:213], v[8:9]
	v_pk_add_f32 v[10:11], v[214:215], v[10:11]
	v_pk_add_f32 v[0:1], v[212:213], v[0:1]
	v_pk_add_f32 v[2:3], v[214:215], v[2:3]
	v_mul_f32_e32 v28, 0xbfb8aa3b, v176
	v_mul_f32_e32 v29, 0xbfb8aa3b, v177
	v_mul_f32_e32 v30, 0xbfb8aa3b, v178
	v_mul_f32_e32 v31, 0xbfb8aa3b, v179
	v_mul_f32_e32 v20, 0xbfb8aa3b, v180
	v_mul_f32_e32 v21, 0xbfb8aa3b, v181
	v_mul_f32_e32 v22, 0xbfb8aa3b, v182
	v_mul_f32_e32 v23, 0xbfb8aa3b, v183
	v_mul_f32_e32 v12, 0xbfb8aa3b, v184
	v_mul_f32_e32 v13, 0xbfb8aa3b, v185
	v_mul_f32_e32 v14, 0xbfb8aa3b, v186
	v_mul_f32_e32 v15, 0xbfb8aa3b, v187
	v_mul_f32_e32 v4, 0xbfb8aa3b, v224
	v_mul_f32_e32 v5, 0xbfb8aa3b, v225
	v_mul_f32_e32 v6, 0xbfb8aa3b, v226
	v_mul_f32_e32 v7, 0xbfb8aa3b, v227
	v_exp_f32_e32 v28, v28
	v_exp_f32_e32 v29, v29
	v_exp_f32_e32 v30, v30
	v_exp_f32_e32 v31, v31
	v_exp_f32_e32 v20, v20
	v_exp_f32_e32 v21, v21
	v_exp_f32_e32 v22, v22
	v_exp_f32_e32 v23, v23
	v_exp_f32_e32 v12, v12
	v_exp_f32_e32 v13, v13
	v_exp_f32_e32 v14, v14
	v_exp_f32_e32 v15, v15
	v_exp_f32_e32 v4, v4
	v_exp_f32_e32 v5, v5
	v_exp_f32_e32 v6, v6
	v_exp_f32_e32 v7, v7
	v_add_f32_e32 v28, 1.0, v28
	v_add_f32_e32 v29, 1.0, v29
	v_add_f32_e32 v30, 1.0, v30
	v_add_f32_e32 v31, 1.0, v31
	v_add_f32_e32 v20, 1.0, v20
	v_add_f32_e32 v21, 1.0, v21
	v_add_f32_e32 v22, 1.0, v22
	v_add_f32_e32 v23, 1.0, v23
	v_add_f32_e32 v12, 1.0, v12
	v_add_f32_e32 v13, 1.0, v13
	v_add_f32_e32 v14, 1.0, v14
	v_add_f32_e32 v15, 1.0, v15
	v_add_f32_e32 v4, 1.0, v4
	v_add_f32_e32 v5, 1.0, v5
	v_add_f32_e32 v6, 1.0, v6
	v_add_f32_e32 v7, 1.0, v7
	v_rcp_f32_e32 v28, v28
	v_rcp_f32_e32 v29, v29
	v_rcp_f32_e32 v30, v30
	v_rcp_f32_e32 v31, v31
	v_rcp_f32_e32 v20, v20
	v_rcp_f32_e32 v21, v21
	v_rcp_f32_e32 v22, v22
	v_rcp_f32_e32 v23, v23
	v_rcp_f32_e32 v12, v12
	v_rcp_f32_e32 v13, v13
	v_rcp_f32_e32 v14, v14
	v_rcp_f32_e32 v15, v15
	v_rcp_f32_e32 v4, v4
	v_rcp_f32_e32 v5, v5
	v_rcp_f32_e32 v6, v6
	v_rcp_f32_e32 v7, v7
	v_pk_mul_f32 v[176:177], v[176:177], v[28:29]
	v_pk_mul_f32 v[178:179], v[178:179], v[30:31]
	v_pk_mul_f32 v[180:181], v[180:181], v[20:21]
	v_pk_mul_f32 v[182:183], v[182:183], v[22:23]
	v_pk_mul_f32 v[184:185], v[184:185], v[12:13]
	v_pk_mul_f32 v[186:187], v[186:187], v[14:15]
	v_pk_mul_f32 v[224:225], v[224:225], v[4:5]
	v_pk_mul_f32 v[226:227], v[226:227], v[6:7]
	v_pk_mul_f32 v[176:177], v[24:25], v[176:177]
	v_pk_mul_f32 v[178:179], v[26:27], v[178:179]
	v_pk_mul_f32 v[180:181], v[16:17], v[180:181]
	v_pk_mul_f32 v[182:183], v[18:19], v[182:183]
	v_pk_mul_f32 v[184:185], v[8:9], v[184:185]
	v_pk_mul_f32 v[186:187], v[10:11], v[186:187]
	v_pk_mul_f32 v[224:225], v[0:1], v[224:225]
	v_pk_mul_f32 v[226:227], v[2:3], v[226:227]
	v_cvt_pk_bf16_f32 v94, v176, v177
	v_cvt_pk_bf16_f32 v95, v178, v179
	v_cvt_pk_bf16_f32 v86, v180, v181
	v_cvt_pk_bf16_f32 v87, v182, v183
	v_cvt_pk_bf16_f32 v78, v184, v185
	v_cvt_pk_bf16_f32 v79, v186, v187
	v_cvt_pk_bf16_f32 v70, v224, v225
	v_cvt_pk_bf16_f32 v71, v226, v227
	s_nop 1
	v_permlane16_swap_b32_e32 v92, v94
	v_permlane16_swap_b32_e32 v93, v95
	v_permlane16_swap_b32_e32 v84, v86
	v_permlane16_swap_b32_e32 v85, v87
	v_permlane16_swap_b32_e32 v76, v78
	v_permlane16_swap_b32_e32 v77, v79
	v_permlane16_swap_b32_e32 v68, v70
	v_permlane16_swap_b32_e32 v69, v71
	global_store_dwordx4 v174, v[92:95], s[0:1]
	v_add_u32_e32 v175, 0x2c00, v174
	global_store_dwordx4 v175, v[84:87], s[0:1]
	v_add_u32_e32 v175, 0x5800, v174
	global_store_dwordx4 v175, v[76:79], s[0:1]
	v_add_u32_e32 v175, 0x8400, v174
	global_store_dwordx4 v175, v[68:71], s[0:1]
	v_lshl_or_b32 v170, s16, 7, v204
	v_lshlrev_b32_e32 v171, 2, v170
	v_add_u32_e32 v172, 0x5800, v171
	global_load_dwordx4 v[230:233], v172, s[56:57]
	global_load_dwordx4 v[234:237], v172, s[12:13]
	global_load_dwordx4 v[238:241], v172, s[14:15]
	global_load_dwordx4 v[242:245], v172, s[58:59]
	global_load_dwordx4 v[246:249], v171, s[56:57]
	global_load_dwordx4 v[250:253], v171, s[12:13]
	s_mov_b32 s98, 1
	s_andn2_b64 vcc, exec, s[20:21]
	s_mov_b64 s[20:21], -1
	s_cbranch_vccnz .LBB0_1795
	s_andn2_b64 vcc, exec, s[2:3]
	s_cbranch_vccnz .LBB0_1794
	s_barrier
	s_branch .LBB0_1794
